# P2 wave units: the four 16-byte loads of each unrolled loop trip issued together with counted vmcnt waits (was one load then vmcnt(0) each)
# baseline (speedup 1.0000x reference)
; __device__ __forceinline__ float bf_lo(unsigned w) { return __uint_as_float(w << 16); }
; __device__ __forceinline__ float bf_hi(unsigned w) { return __uint_as_float(w & 0xffff0000u); }
; __device__ __forceinline__ void p2_wave_unit(int u, const bf16_t* H, float* kmean, unsigned* ctl, int lane) {
;     ...
;         float mq = 0.f, mk = 0.f;
; #pragma unroll 4
;         for (int it = 0; it < 32; ++it) { const u32x4 wq = *(const u32x4*)(base + (size_t)it * 8 * HQ + C_FQ), wk = *(const u32x4*)(base + (size_t)it * 8 * HQ + C_FK);
;             float a = bf_lo(wq.x) * bf_lo(wq.x) + bf_hi(wq.x) * bf_hi(wq.x) + bf_lo(wq.y) * bf_lo(wq.y) + bf_hi(wq.y) * bf_hi(wq.y) + bf_lo(wq.z) * bf_lo(wq.z) + bf_hi(wq.z) * bf_hi(wq.z) + bf_lo(wq.w) * bf_lo(wq.w) + bf_hi(wq.w) * bf_hi(wq.w);
;             float c = bf_lo(wk.x) * bf_lo(wk.x) + bf_hi(wk.x) * bf_hi(wk.x) + bf_lo(wk.y) * bf_lo(wk.y) + bf_hi(wk.y) * bf_hi(wk.y) + bf_lo(wk.z) * bf_lo(wk.z) + bf_hi(wk.z) * bf_hi(wk.z) + bf_lo(wk.w) * bf_lo(wk.w) + bf_hi(wk.w) * bf_hi(wk.w);
;             a += __shfl_xor(a, 1); a += __shfl_xor(a, 2); a += __shfl_xor(a, 4); c += __shfl_xor(c, 1); c += __shfl_xor(c, 2); c += __shfl_xor(c, 4);
;             mq = fmaxf(mq, a); mk = fmaxf(mk, c); }
;         mq = wave_max(mq); mk = wave_max(mk);
;         if (lane == 0) { atomicMax(ctl + 1024 + bh, __float_as_uint(mq)); atomicMax(ctl + 1040 + bh, __float_as_uint(mk)); }
.LBB0_198:
	v_lshl_add_u64 v[8:9], v[6:7], 0, s[18:19]
	s_waitcnt vmcnt(0)
	s_mov_b64 s[98:99], 0x20800000
	v_lshl_add_u64 v[104:105], v[8:9], 0, s[98:99]
	global_load_dwordx4 v[72:75], v[104:105], off
	global_load_dwordx4 v[76:79], v[104:105], off offset:1024
	s_mov_b64 s[98:99], 0x20815000
	v_lshl_add_u64 v[104:105], v[8:9], 0, s[98:99]
	global_load_dwordx4 v[80:83], v[104:105], off
	global_load_dwordx4 v[84:87], v[104:105], off offset:1024
	s_mov_b64 s[98:99], 0x2082a000
	v_lshl_add_u64 v[104:105], v[8:9], 0, s[98:99]
	global_load_dwordx4 v[88:91], v[104:105], off
	global_load_dwordx4 v[92:95], v[104:105], off offset:1024
	s_mov_b64 s[98:99], 0x2083f000
	v_lshl_add_u64 v[104:105], v[8:9], 0, s[98:99]
	global_load_dwordx4 v[96:99], v[104:105], off
	global_load_dwordx4 v[100:103], v[104:105], off offset:1024
	v_add_co_u32_e32 v16, vcc, 0x20800000, v8
	s_mov_b32 s5, 0x20815000
	s_nop 0
	v_addc_co_u32_e32 v17, vcc, 0, v9, vcc
	s_nop 0
	s_add_u32 s18, s18, 0x54000
	s_addc_u32 s19, s19, 0
	s_cmp_eq_u32 s18, 0x2a0000
	s_waitcnt vmcnt(7)
	v_mov_b32_e32 v12, v72
	v_mov_b32_e32 v13, v73
	v_mov_b32_e32 v14, v74
	v_mov_b32_e32 v15, v75
	v_lshlrev_b32_e32 v20, 16, v12
	v_and_b32_e32 v21, 0xffff0000, v12
	v_pk_mul_f32 v[20:21], v[20:21], v[20:21]
	v_and_b32_e32 v12, 0xffff0000, v13
	v_lshlrev_b32_e32 v13, 16, v13
	v_pk_mul_f32 v[12:13], v[12:13], v[12:13]
	v_add_f32_e32 v20, v20, v21
	v_and_b32_e32 v24, 0xffff0000, v14
	v_lshlrev_b32_e32 v25, 16, v14
	v_add_f32_e32 v13, v13, v20
	v_pk_mul_f32 v[24:25], v[24:25], v[24:25]
	v_add_f32_e32 v12, v12, v13
	v_and_b32_e32 v14, 0xffff0000, v15
	v_lshlrev_b32_e32 v15, 16, v15
	v_add_f32_e32 v12, v25, v12
	v_pk_mul_f32 v[14:15], v[14:15], v[14:15]
	v_add_f32_e32 v12, v24, v12
	v_add_f32_e32 v12, v15, v12
	v_add_f32_e32 v20, v14, v12
	s_waitcnt vmcnt(6)
	v_mov_b32_e32 v16, v76
	v_mov_b32_e32 v17, v77
	v_mov_b32_e32 v18, v78
	v_mov_b32_e32 v19, v79
	v_lshlrev_b32_e32 v12, 16, v16
	v_and_b32_e32 v13, 0xffff0000, v16
	v_pk_mul_f32 v[12:13], v[12:13], v[12:13]
	v_and_b32_e32 v14, 0xffff0000, v17
	v_add_f32_e32 v12, v12, v13
	ds_bpermute_b32 v13, v226, v20
	v_lshlrev_b32_e32 v15, 16, v17
	v_pk_mul_f32 v[14:15], v[14:15], v[14:15]
	v_and_b32_e32 v16, 0xffff0000, v18
	v_add_f32_e32 v12, v15, v12
	s_waitcnt lgkmcnt(0)
	v_add_f32_e32 v13, v20, v13
	v_add_f32_e32 v12, v14, v12
	ds_bpermute_b32 v14, v227, v13
	v_lshlrev_b32_e32 v17, 16, v18
	v_pk_mul_f32 v[16:17], v[16:17], v[16:17]
	v_and_b32_e32 v18, 0xffff0000, v19
	v_lshlrev_b32_e32 v19, 16, v19
	s_waitcnt lgkmcnt(0)
	v_add_f32_e32 v13, v13, v14
	ds_bpermute_b32 v14, v228, v13
	v_add_f32_e32 v12, v17, v12
	v_pk_mul_f32 v[18:19], v[18:19], v[18:19]
	v_add_f32_e32 v12, v16, v12
	v_add_f32_e32 v12, v19, v12
	v_add_f32_e32 v12, v18, v12
	s_waitcnt lgkmcnt(0)
	v_add_f32_e32 v23, v13, v14
	ds_bpermute_b32 v13, v226, v12
	v_add_co_u32_e32 v16, vcc, s5, v8
	s_mov_b32 s5, 0x2082a000
	s_nop 0
	v_addc_co_u32_e32 v17, vcc, 0, v9, vcc
	s_waitcnt lgkmcnt(0)
	v_add_f32_e32 v12, v12, v13
	ds_bpermute_b32 v13, v227, v12
	s_waitcnt lgkmcnt(0)
	v_add_f32_e32 v12, v12, v13
	ds_bpermute_b32 v13, v228, v12
	s_waitcnt lgkmcnt(0)
	v_add_f32_e32 v26, v12, v13
	s_nop 0
	s_waitcnt vmcnt(5)
	v_mov_b32_e32 v12, v80
	v_mov_b32_e32 v13, v81
	v_mov_b32_e32 v14, v82
	v_mov_b32_e32 v15, v83
	v_lshlrev_b32_e32 v20, 16, v12
	v_and_b32_e32 v21, 0xffff0000, v12
	v_pk_mul_f32 v[20:21], v[20:21], v[20:21]
	v_and_b32_e32 v12, 0xffff0000, v13
	v_lshlrev_b32_e32 v13, 16, v13
	v_pk_mul_f32 v[12:13], v[12:13], v[12:13]
	v_add_f32_e32 v20, v20, v21
	v_and_b32_e32 v24, 0xffff0000, v14
	v_lshlrev_b32_e32 v25, 16, v14
	v_add_f32_e32 v13, v13, v20
	v_pk_mul_f32 v[24:25], v[24:25], v[24:25]
	v_add_f32_e32 v12, v12, v13
	v_and_b32_e32 v14, 0xffff0000, v15
	v_lshlrev_b32_e32 v15, 16, v15
	v_add_f32_e32 v12, v25, v12
	v_pk_mul_f32 v[14:15], v[14:15], v[14:15]
	v_add_f32_e32 v12, v24, v12
	v_add_f32_e32 v12, v15, v12
	v_add_f32_e32 v20, v14, v12
	s_waitcnt vmcnt(4)
	v_mov_b32_e32 v16, v84
	v_mov_b32_e32 v17, v85
	v_mov_b32_e32 v18, v86
	v_mov_b32_e32 v19, v87
	v_lshlrev_b32_e32 v12, 16, v16
	v_and_b32_e32 v13, 0xffff0000, v16
	v_pk_mul_f32 v[12:13], v[12:13], v[12:13]
	v_and_b32_e32 v14, 0xffff0000, v17
	v_add_f32_e32 v12, v12, v13
	ds_bpermute_b32 v13, v226, v20
	v_lshlrev_b32_e32 v15, 16, v17
	v_pk_mul_f32 v[14:15], v[14:15], v[14:15]
	v_and_b32_e32 v16, 0xffff0000, v18
	v_add_f32_e32 v12, v15, v12
	s_waitcnt lgkmcnt(0)
	v_add_f32_e32 v13, v20, v13
	v_add_f32_e32 v12, v14, v12
	ds_bpermute_b32 v14, v227, v13
	v_lshlrev_b32_e32 v17, 16, v18
	v_pk_mul_f32 v[16:17], v[16:17], v[16:17]
	v_and_b32_e32 v18, 0xffff0000, v19
	v_lshlrev_b32_e32 v19, 16, v19
	s_waitcnt lgkmcnt(0)
	v_add_f32_e32 v13, v13, v14
	ds_bpermute_b32 v14, v228, v13
	v_add_f32_e32 v12, v17, v12
	v_pk_mul_f32 v[18:19], v[18:19], v[18:19]
	v_add_f32_e32 v12, v16, v12
	v_add_f32_e32 v12, v19, v12
	v_add_f32_e32 v12, v18, v12
	s_waitcnt lgkmcnt(0)
	v_add_f32_e32 v13, v13, v14
	ds_bpermute_b32 v14, v226, v12
	v_max3_f32 v23, v10, v23, v13
	s_waitcnt lgkmcnt(0)
	v_add_f32_e32 v12, v12, v14
	ds_bpermute_b32 v14, v227, v12
	s_waitcnt lgkmcnt(0)
	v_add_f32_e32 v12, v12, v14
	ds_bpermute_b32 v14, v228, v12
	s_waitcnt lgkmcnt(0)
	v_add_f32_e32 v12, v12, v14
	v_add_co_u32_e32 v14, vcc, s5, v8
	v_max3_f32 v24, v11, v26, v12
	s_nop 0
	v_addc_co_u32_e32 v15, vcc, 0, v9, vcc
	s_nop 0
	s_mov_b32 s5, 0x2083f000
	s_waitcnt vmcnt(3)
; __device__ __forceinline__ float bf_lo(unsigned w) { return __uint_as_float(w << 16); }
; __device__ __forceinline__ float bf_hi(unsigned w) { return __uint_as_float(w & 0xffff0000u); }
; __device__ __forceinline__ void p2_wave_unit(int u, const bf16_t* H, float* kmean, unsigned* ctl, int lane) {
;     ...
;         for (int it = 0; it < 32; ++it) { const u32x4 wq = *(const u32x4*)(base + (size_t)it * 8 * HQ + C_FQ), wk = *(const u32x4*)(base + (size_t)it * 8 * HQ + C_FK);
;             float a = bf_lo(wq.x) * bf_lo(wq.x) + bf_hi(wq.x) * bf_hi(wq.x) + bf_lo(wq.y) * bf_lo(wq.y) + bf_hi(wq.y) * bf_hi(wq.y) + bf_lo(wq.z) * bf_lo(wq.z) + bf_hi(wq.z) * bf_hi(wq.z) + bf_lo(wq.w) * bf_lo(wq.w) + bf_hi(wq.w) * bf_hi(wq.w);
;             float c = bf_lo(wk.x) * bf_lo(wk.x) + bf_hi(wk.x) * bf_hi(wk.x) + bf_lo(wk.y) * bf_lo(wk.y) + bf_hi(wk.y) * bf_hi(wk.y) + bf_lo(wk.z) * bf_lo(wk.z) + bf_hi(wk.z) * bf_hi(wk.z) + bf_lo(wk.w) * bf_lo(wk.w) + bf_hi(wk.w) * bf_hi(wk.w);
;             a += __shfl_xor(a, 1); a += __shfl_xor(a, 2); a += __shfl_xor(a, 4); c += __shfl_xor(c, 1); c += __shfl_xor(c, 2); c += __shfl_xor(c, 4);
;             mq = fmaxf(mq, a); mk = fmaxf(mk, c); }
;         mq = wave_max(mq); mk = wave_max(mk);
;         if (lane == 0) { atomicMax(ctl + 1024 + bh, __float_as_uint(mq)); atomicMax(ctl + 1040 + bh, __float_as_uint(mk)); }
	v_mov_b32_e32 v10, v88
	v_mov_b32_e32 v11, v89
	v_mov_b32_e32 v12, v90
	v_mov_b32_e32 v13, v91
	v_lshlrev_b32_e32 v18, 16, v10
	v_and_b32_e32 v19, 0xffff0000, v10
	v_pk_mul_f32 v[18:19], v[18:19], v[18:19]
	v_and_b32_e32 v10, 0xffff0000, v11
	v_lshlrev_b32_e32 v11, 16, v11
	v_pk_mul_f32 v[10:11], v[10:11], v[10:11]
	v_add_f32_e32 v18, v18, v19
	v_and_b32_e32 v20, 0xffff0000, v12
	v_lshlrev_b32_e32 v21, 16, v12
	v_add_f32_e32 v11, v11, v18
	v_pk_mul_f32 v[20:21], v[20:21], v[20:21]
	v_add_f32_e32 v10, v10, v11
	v_and_b32_e32 v12, 0xffff0000, v13
	v_lshlrev_b32_e32 v13, 16, v13
	v_add_f32_e32 v10, v21, v10
	v_pk_mul_f32 v[12:13], v[12:13], v[12:13]
	v_add_f32_e32 v10, v20, v10
	v_add_f32_e32 v10, v13, v10
	v_add_f32_e32 v18, v12, v10
	s_waitcnt vmcnt(2)
	v_mov_b32_e32 v14, v92
	v_mov_b32_e32 v15, v93
	v_mov_b32_e32 v16, v94
	v_mov_b32_e32 v17, v95
	v_lshlrev_b32_e32 v10, 16, v14
	v_and_b32_e32 v11, 0xffff0000, v14
	v_pk_mul_f32 v[10:11], v[10:11], v[10:11]
	v_and_b32_e32 v12, 0xffff0000, v15
	v_add_f32_e32 v10, v10, v11
	ds_bpermute_b32 v11, v226, v18
	v_lshlrev_b32_e32 v13, 16, v15
	v_pk_mul_f32 v[12:13], v[12:13], v[12:13]
	v_and_b32_e32 v14, 0xffff0000, v16
	v_add_f32_e32 v10, v13, v10
	s_waitcnt lgkmcnt(0)
	v_add_f32_e32 v11, v18, v11
	v_add_f32_e32 v10, v12, v10
	ds_bpermute_b32 v12, v227, v11
	v_lshlrev_b32_e32 v15, 16, v16
	v_pk_mul_f32 v[14:15], v[14:15], v[14:15]
	v_and_b32_e32 v16, 0xffff0000, v17
	v_lshlrev_b32_e32 v17, 16, v17
	s_waitcnt lgkmcnt(0)
	v_add_f32_e32 v11, v11, v12
	ds_bpermute_b32 v12, v228, v11
	v_add_f32_e32 v10, v15, v10
	v_pk_mul_f32 v[16:17], v[16:17], v[16:17]
	v_add_f32_e32 v10, v14, v10
	v_add_f32_e32 v10, v17, v10
	v_add_f32_e32 v10, v16, v10
	s_waitcnt lgkmcnt(0)
	v_add_f32_e32 v20, v11, v12
	ds_bpermute_b32 v11, v226, v10
	v_add_co_u32_e32 v12, vcc, s5, v8
	s_waitcnt lgkmcnt(0)
	v_add_f32_e32 v10, v10, v11
	ds_bpermute_b32 v11, v227, v10
	v_addc_co_u32_e32 v13, vcc, 0, v9, vcc
	s_waitcnt lgkmcnt(0)
	v_add_f32_e32 v10, v10, v11
	ds_bpermute_b32 v11, v228, v10
	s_waitcnt lgkmcnt(0)
	v_add_f32_e32 v21, v10, v11
	s_nop 0
	s_waitcnt vmcnt(1)
	v_mov_b32_e32 v8, v96
	v_mov_b32_e32 v9, v97
	v_mov_b32_e32 v10, v98
	v_mov_b32_e32 v11, v99
	v_lshlrev_b32_e32 v16, 16, v8
	v_and_b32_e32 v17, 0xffff0000, v8
	v_pk_mul_f32 v[16:17], v[16:17], v[16:17]
	v_and_b32_e32 v8, 0xffff0000, v9
	v_lshlrev_b32_e32 v9, 16, v9
	v_pk_mul_f32 v[8:9], v[8:9], v[8:9]
	v_add_f32_e32 v16, v16, v17
	v_and_b32_e32 v18, 0xffff0000, v10
	v_lshlrev_b32_e32 v19, 16, v10
	v_add_f32_e32 v9, v9, v16
	v_pk_mul_f32 v[18:19], v[18:19], v[18:19]
	v_add_f32_e32 v8, v8, v9
	v_and_b32_e32 v10, 0xffff0000, v11
	v_lshlrev_b32_e32 v11, 16, v11
	v_add_f32_e32 v8, v19, v8
	v_pk_mul_f32 v[10:11], v[10:11], v[10:11]
	v_add_f32_e32 v8, v18, v8
	v_add_f32_e32 v8, v11, v8
	v_add_f32_e32 v16, v10, v8
	s_waitcnt vmcnt(0)
	v_mov_b32_e32 v12, v100
	v_mov_b32_e32 v13, v101
	v_mov_b32_e32 v14, v102
	v_mov_b32_e32 v15, v103
	v_lshlrev_b32_e32 v8, 16, v12
	v_and_b32_e32 v9, 0xffff0000, v12
	v_pk_mul_f32 v[8:9], v[8:9], v[8:9]
	v_and_b32_e32 v10, 0xffff0000, v13
	v_add_f32_e32 v8, v8, v9
	ds_bpermute_b32 v9, v226, v16
	v_lshlrev_b32_e32 v11, 16, v13
	v_pk_mul_f32 v[10:11], v[10:11], v[10:11]
	v_and_b32_e32 v12, 0xffff0000, v14
	v_add_f32_e32 v8, v11, v8
	s_waitcnt lgkmcnt(0)
	v_add_f32_e32 v9, v16, v9
	v_add_f32_e32 v8, v10, v8
	ds_bpermute_b32 v10, v227, v9
	v_lshlrev_b32_e32 v13, 16, v14
	v_pk_mul_f32 v[12:13], v[12:13], v[12:13]
	v_and_b32_e32 v14, 0xffff0000, v15
	v_lshlrev_b32_e32 v15, 16, v15
	s_waitcnt lgkmcnt(0)
	v_add_f32_e32 v9, v9, v10
	ds_bpermute_b32 v10, v228, v9
	v_add_f32_e32 v8, v13, v8
	v_pk_mul_f32 v[14:15], v[14:15], v[14:15]
	v_add_f32_e32 v8, v12, v8
	v_add_f32_e32 v8, v15, v8
	v_add_f32_e32 v8, v14, v8
	s_waitcnt lgkmcnt(0)
	v_add_f32_e32 v9, v9, v10
	ds_bpermute_b32 v10, v226, v8
	s_waitcnt lgkmcnt(0)
	v_add_f32_e32 v8, v8, v10
	ds_bpermute_b32 v10, v227, v8
	s_waitcnt lgkmcnt(0)
	v_add_f32_e32 v8, v8, v10
	ds_bpermute_b32 v10, v228, v8
	s_waitcnt lgkmcnt(0)
	v_add_f32_e32 v8, v8, v10
	v_max3_f32 v10, v23, v20, v9
	v_max3_f32 v11, v24, v21, v8
	s_cbranch_scc0 .LBB0_198
	ds_bpermute_b32 v6, v226, v10
	ds_bpermute_b32 v7, v226, v11
	v_max_f32_e32 v8, v10, v10
	v_max_f32_e32 v9, v11, v11
	s_waitcnt lgkmcnt(1)
	v_max_f32_e32 v6, v6, v6
	s_waitcnt lgkmcnt(0)
	v_max_f32_e32 v7, v7, v7
	v_max_f32_e32 v6, v8, v6
	v_max_f32_e32 v7, v9, v7
	ds_bpermute_b32 v8, v227, v6
	ds_bpermute_b32 v9, v227, v7
	s_waitcnt lgkmcnt(1)
	v_max_f32_e32 v8, v8, v8
	s_waitcnt lgkmcnt(0)
	v_max_f32_e32 v9, v9, v9
	v_max_f32_e32 v6, v6, v8
	v_max_f32_e32 v7, v7, v9
	ds_bpermute_b32 v8, v228, v6
	ds_bpermute_b32 v9, v228, v7
	s_waitcnt lgkmcnt(1)
	v_max_f32_e32 v8, v8, v8
	s_waitcnt lgkmcnt(0)
	v_max_f32_e32 v9, v9, v9
	v_max_f32_e32 v6, v6, v8
	v_max_f32_e32 v7, v7, v9
	ds_bpermute_b32 v8, v229, v6
	ds_bpermute_b32 v9, v229, v7
	s_waitcnt lgkmcnt(1)
	v_max_f32_e32 v8, v8, v8
	s_waitcnt lgkmcnt(0)
	v_max_f32_e32 v9, v9, v9
	v_max_f32_e32 v6, v6, v8
	v_max_f32_e32 v7, v7, v9
	ds_bpermute_b32 v8, v230, v6
	ds_bpermute_b32 v9, v230, v7
	s_waitcnt lgkmcnt(1)
	v_max_f32_e32 v8, v8, v8
	s_waitcnt lgkmcnt(0)
	v_max_f32_e32 v9, v9, v9
	v_max_f32_e32 v8, v6, v8
	v_max_f32_e32 v6, v7, v9
	ds_bpermute_b32 v9, v231, v8
	ds_bpermute_b32 v7, v231, v6
	s_and_saveexec_b64 s[18:19], s[38:39]
	s_cbranch_execz .LBB0_208
	s_waitcnt lgkmcnt(1)
	v_max_f32_e32 v9, v9, v9
	v_max_f32_e32 v8, v8, v8
	s_mov_b64 s[28:29], exec
	v_max_f32_e32 v8, v8, v9
	s_mov_b32 s5, 0

; __device__ __forceinline__ float bf_lo(unsigned w) { return __uint_as_float(w << 16); }
; __device__ __forceinline__ float bf_hi(unsigned w) { return __uint_as_float(w & 0xffff0000u); }
; __device__ __forceinline__ void p2_wave_unit(int u, const bf16_t* H, float* kmean, unsigned* ctl, int lane) {
;     ...
;         float s[8] = {0.f, 0.f, 0.f, 0.f, 0.f, 0.f, 0.f, 0.f};
; #pragma unroll 4
;         for (int it = 0; it < 32; ++it) { const u32x4 w = *(const u32x4*)(base + (size_t)it * 8 * HQ + C_MK);
;             s[0] += bf_lo(w.x); s[1] += bf_hi(w.x); s[2] += bf_lo(w.y); s[3] += bf_hi(w.y); s[4] += bf_lo(w.z); s[5] += bf_hi(w.z); s[6] += bf_lo(w.w); s[7] += bf_hi(w.w); }
; #pragma unroll
;         for (int i = 0; i < 8; ++i) { s[i] += __shfl_xor(s[i], 8); s[i] += __shfl_xor(s[i], 16); s[i] += __shfl_xor(s[i], 32); }
;         if (rs == 0) { float* d = kmean + ((size_t)bh * 64 + blk) * 64 + ch * 8; f32x4 o0 = {s[0], s[1], s[2], s[3]}, o1 = {s[4], s[5], s[6], s[7]}; *(f32x4*)d = o0 * (1.f / 256.f); *(f32x4*)(d + 4) = o1 * (1.f / 256.f); }
.LBB0_211:
	v_lshl_add_u64 v[16:17], v[6:7], 0, s[18:19]
	s_waitcnt vmcnt(0)
	s_mov_b64 s[98:99], 0x20801000
	v_lshl_add_u64 v[70:71], v[16:17], 0, s[98:99]
	global_load_dwordx4 v[54:57], v[70:71], off offset:3584
	s_mov_b64 s[98:99], 0x20816000
	v_lshl_add_u64 v[70:71], v[16:17], 0, s[98:99]
	global_load_dwordx4 v[58:61], v[70:71], off offset:3584
	s_mov_b64 s[98:99], 0x2082b000
	v_lshl_add_u64 v[70:71], v[16:17], 0, s[98:99]
	global_load_dwordx4 v[62:65], v[70:71], off offset:3584
	s_mov_b64 s[98:99], 0x20840000
	v_lshl_add_u64 v[70:71], v[16:17], 0, s[98:99]
	global_load_dwordx4 v[66:69], v[70:71], off offset:3584
	v_add_co_u32_e32 v18, vcc, 0x20801000, v16
	s_mov_b32 s4, 0x20816000
	s_nop 0
	v_addc_co_u32_e32 v19, vcc, 0, v17, vcc
	s_add_u32 s18, s18, 0x54000
	s_addc_u32 s19, s19, 0
	s_cmp_eq_u32 s18, 0x2a0000
	s_waitcnt vmcnt(3)
	v_mov_b32_e32 v18, v54
	v_mov_b32_e32 v19, v55
	v_mov_b32_e32 v20, v56
	v_mov_b32_e32 v21, v57
	v_lshlrev_b32_e32 v24, 16, v18
	v_and_b32_e32 v25, 0xffff0000, v18
	v_lshlrev_b32_e32 v18, 16, v19
	v_and_b32_e32 v19, 0xffff0000, v19
	v_pk_add_f32 v[12:13], v[12:13], v[18:19]
	v_lshlrev_b32_e32 v18, 16, v20
	v_and_b32_e32 v19, 0xffff0000, v20
	v_pk_add_f32 v[18:19], v[10:11], v[18:19]
	v_lshlrev_b32_e32 v10, 16, v21
	v_and_b32_e32 v11, 0xffff0000, v21
	v_pk_add_f32 v[20:21], v[8:9], v[10:11]
	v_add_co_u32_e32 v8, vcc, s4, v16
	v_pk_add_f32 v[14:15], v[14:15], v[24:25]
	s_nop 0
	v_addc_co_u32_e32 v9, vcc, 0, v17, vcc
	s_mov_b32 s4, 0x2082b000
	s_waitcnt vmcnt(2)
	v_mov_b32_e32 v8, v58
	v_mov_b32_e32 v9, v59
	v_mov_b32_e32 v10, v60
	v_mov_b32_e32 v11, v61
	v_lshlrev_b32_e32 v24, 16, v8
	v_and_b32_e32 v25, 0xffff0000, v8
	v_lshlrev_b32_e32 v8, 16, v9
	v_and_b32_e32 v9, 0xffff0000, v9
	v_pk_add_f32 v[12:13], v[12:13], v[8:9]
	v_lshlrev_b32_e32 v8, 16, v10
	v_and_b32_e32 v9, 0xffff0000, v10
	v_pk_add_f32 v[18:19], v[18:19], v[8:9]
	v_lshlrev_b32_e32 v8, 16, v11
	v_and_b32_e32 v9, 0xffff0000, v11
	v_pk_add_f32 v[20:21], v[20:21], v[8:9]
	v_add_co_u32_e32 v8, vcc, s4, v16
	v_pk_add_f32 v[14:15], v[14:15], v[24:25]
	s_nop 0
	v_addc_co_u32_e32 v9, vcc, 0, v17, vcc
	s_mov_b32 s4, 0x20840000
	s_waitcnt vmcnt(1)
	v_mov_b32_e32 v8, v62
	v_mov_b32_e32 v9, v63
	v_mov_b32_e32 v10, v64
	v_mov_b32_e32 v11, v65
	v_lshlrev_b32_e32 v24, 16, v8
	v_and_b32_e32 v25, 0xffff0000, v8
	v_lshlrev_b32_e32 v8, 16, v9
	v_and_b32_e32 v9, 0xffff0000, v9
	v_pk_add_f32 v[8:9], v[12:13], v[8:9]
	v_lshlrev_b32_e32 v12, 16, v10
	v_and_b32_e32 v13, 0xffff0000, v10
	v_lshlrev_b32_e32 v10, 16, v11
	v_and_b32_e32 v11, 0xffff0000, v11
	v_pk_add_f32 v[20:21], v[20:21], v[10:11]
	v_add_co_u32_e32 v10, vcc, s4, v16
	v_pk_add_f32 v[14:15], v[14:15], v[24:25]
	s_nop 0
	v_addc_co_u32_e32 v11, vcc, 0, v17, vcc
	v_pk_add_f32 v[24:25], v[18:19], v[12:13]
	s_waitcnt vmcnt(0)
	v_mov_b32_e32 v16, v66
	v_mov_b32_e32 v17, v67
	v_mov_b32_e32 v18, v68
	v_mov_b32_e32 v19, v69
	v_lshlrev_b32_e32 v10, 16, v16
	v_and_b32_e32 v11, 0xffff0000, v16
	v_pk_add_f32 v[14:15], v[14:15], v[10:11]
	v_lshlrev_b32_e32 v10, 16, v17
	v_and_b32_e32 v11, 0xffff0000, v17
	v_pk_add_f32 v[12:13], v[8:9], v[10:11]
	v_lshlrev_b32_e32 v8, 16, v18
	v_and_b32_e32 v9, 0xffff0000, v18
	v_pk_add_f32 v[10:11], v[24:25], v[8:9]
	v_lshlrev_b32_e32 v8, 16, v19
	v_and_b32_e32 v9, 0xffff0000, v19
	v_pk_add_f32 v[8:9], v[20:21], v[8:9]
	s_cbranch_scc0 .LBB0_211
	ds_bpermute_b32 v6, v229, v14
	ds_bpermute_b32 v7, v229, v15
	ds_bpermute_b32 v16, v229, v12
	ds_bpermute_b32 v17, v229, v13
	ds_bpermute_b32 v20, v229, v10
	ds_bpermute_b32 v21, v229, v11
	s_waitcnt lgkmcnt(4)
	v_pk_add_f32 v[6:7], v[14:15], v[6:7]
	ds_bpermute_b32 v14, v230, v6
	s_waitcnt lgkmcnt(3)
	v_pk_add_f32 v[16:17], v[12:13], v[16:17]
	ds_bpermute_b32 v15, v230, v7
	ds_bpermute_b32 v18, v230, v16
	ds_bpermute_b32 v19, v230, v17
	s_waitcnt lgkmcnt(4)
	v_pk_add_f32 v[10:11], v[10:11], v[20:21]
	ds_bpermute_b32 v20, v230, v10
	s_waitcnt lgkmcnt(3)
	v_pk_add_f32 v[6:7], v[6:7], v[14:15]
	ds_bpermute_b32 v21, v230, v11
	s_waitcnt lgkmcnt(2)
	v_pk_add_f32 v[14:15], v[16:17], v[18:19]
	ds_bpermute_b32 v18, v229, v8
	ds_bpermute_b32 v19, v229, v9
	ds_bpermute_b32 v12, v231, v6
	ds_bpermute_b32 v13, v231, v7
	ds_bpermute_b32 v16, v231, v14
	ds_bpermute_b32 v17, v231, v15
	s_waitcnt lgkmcnt(4)
	v_pk_add_f32 v[18:19], v[8:9], v[18:19]
	ds_bpermute_b32 v24, v230, v18
	ds_bpermute_b32 v25, v230, v19
	v_pk_add_f32 v[8:9], v[10:11], v[20:21]
	ds_bpermute_b32 v10, v231, v8
	ds_bpermute_b32 v11, v231, v9
	s_waitcnt lgkmcnt(2)
	v_pk_add_f32 v[18:19], v[18:19], v[24:25]
	ds_bpermute_b32 v20, v231, v18
	ds_bpermute_b32 v21, v231, v19
	s_and_saveexec_b64 s[18:19], s[40:41]
	s_cbranch_execz .LBB0_194
	v_pk_add_f32 v[24:25], v[6:7], v[12:13]
	v_pk_add_f32 v[12:13], v[14:15], v[16:17]
	s_lshl_b32 s30, s3, 6
	s_mov_b32 s4, 0x3b800000
	s_waitcnt lgkmcnt(2)
	v_pk_add_f32 v[6:7], v[8:9], v[10:11]
	s_waitcnt lgkmcnt(0)
	v_pk_add_f32 v[8:9], v[18:19], v[20:21]
	v_lshl_add_u64 v[14:15], s[30:31], 2, v[2:3]
	v_pk_mul_f32 v[12:13], v[12:13], s[4:5] op_sel_hi:[1,0]
	v_pk_mul_f32 v[10:11], v[24:25], s[4:5] op_sel_hi:[1,0]
	v_pk_mul_f32 v[8:9], v[8:9], s[4:5] op_sel_hi:[1,0]
	v_pk_mul_f32 v[6:7], v[6:7], s[4:5] op_sel_hi:[1,0]
	global_store_dwordx4 v[14:15], v[10:13], off
	global_store_dwordx4 v[14:15], v[6:9], off offset:16
	s_branch .LBB0_194
